# D unit: masked ALiBi offsets kept per unit, scaled by the slope in the masked-tile paths (16 packed mults per sequence instead of 64 compare/select)
# speedup vs baseline: 1.0105x; 1.0066x over previous
; #define LAS __attribute__((address_space(3)))
; DI float fexp2(float x) { return __builtin_amdgcn_exp2f(x); }
; __device__ __forceinline__ unsigned xb_xcc_id() { return (unsigned)__builtin_amdgcn_s_getreg((3 << 11) | 20) & 0xFu; }
; DI void unit_dilated2(int u, const bf16* __restrict__ Q, const bf16* __restrict__ K, const bf16* __restrict__ V, const bf16* __restrict__ G, bf16* __restrict__ MIX, LAS unsigned char* lds, int tid, int lane, int wave) {
;     asm volatile("" : "+v"(lane), "+v"(tid));
;     const int bh = u >> 4, blk = u & 15, b = bh >> 3, h = bh & 7, T0 = blk * 512;
;     const int qq = lane & 31, hh = lane >> 5;
;     LAS unsigned char* kst = lds + DL_STAGE + wave * 8192; LAS unsigned char* vst = kst + 4096;
;     LAS float* lseb = (LAS float*)(lds + DL_LSE);
;     const float slope2 = fexp2(-(float)(h + 1)) * LOG2E;
;     DilWT cw = dil_wt(0, wave, b, h, T0, qq, slope2);
;     bf16x8 qf[4];
; #pragma unroll
;     for (int st = 0; st < 4; ++st) qf[st] = *(const bf16x8*)(Q + cw.qrow * 512 + h * 64 + 16 * st + 8 * hh);
;     v4u kr[4], vr[4];
;     dil_load(kr, vr, K, V, cw.rb0 + (long)(32 * 4) * cw.gstride, cw.gstride, lane);
; __global__ void __launch_bounds__(NT, 2) fwd(Args args) {
;     ...
;             if (tid == 0) { const unsigned myx = xb_xcc_id() & 7u; int got = -1;
;                 for (unsigned k = 0; k < 8u && got < 0; ++k) { const unsigned x = (myx + k) & 7u;
;                     const unsigned v = __hip_atomic_fetch_add(ctl + CW_QD + ((pass * 2 + r2) * 8 + x) * 64, 1u, RLX_AGENT); if (v < 32u) got = (int)(x * 32u + v); }
;                 *slot = got; }
;             __syncthreads();
;             const int u = __builtin_amdgcn_readfirstlane(*slot); if (u < 0) break;
.LBB0_752:
	s_or_b64 exec, exec, s[6:7]
	v_mov_b32_e32 v3, s49
	s_waitcnt lgkmcnt(0)
	s_barrier
	ds_read_b32 v3, v3
	s_waitcnt lgkmcnt(0)
	v_readfirstlane_b32 s0, v3
	s_cmp_lt_i32 s0, 0
	s_cbranch_scc1 .LBB0_786
	s_lshr_b32 s38, s0, 7
	s_bfe_u32 s2, s0, 0x30004
	s_lshl_b32 s0, s0, 9
	s_and_b32 s34, s0, 0x1e00
	s_or_b32 s6, s34, s41
	s_sub_i32 s0, 0x80, s6
	s_lshl_b64 s[12:13], s[38:39], 13
	s_lshr_b32 s7, s0, 5
	s_add_i32 s0, s6, 0xffffff80
	s_add_i32 s3, s2, 1
	s_or_b32 s10, s12, s34
	s_ashr_i32 s1, s0, 31
	v_mov_b32_e32 v3, v182
	v_mov_b32_e32 v227, v0
	s_add_u32 s8, s12, s40
	s_addc_u32 s9, s13, 0
	v_and_b32_e32 v228, 31, v3
	v_or_b32_e32 v4, s41, v228
	s_add_u32 s0, s8, s0
	v_add_u32_e32 v184, s40, v4
	s_mov_b32 s11, s13
	v_mov_b32_e32 v185, v2
	s_addc_u32 s1, s9, s1
	s_lshl_b32 s14, s2, 6
	s_lshl_b32 s38, s2, 7
	v_ashrrev_i32_e32 v14, 5, v3
	v_lshl_add_u64 v[4:5], s[10:11], 0, v[184:185]
	s_cmpk_lt_u32 s6, 0x80
	v_lshlrev_b64 v[4:5], 10, v[4:5]
	v_lshlrev_b32_e32 v6, 3, v14
	s_cselect_b32 s47, s7, 0
	s_lshl_b64 s[16:17], s[0:1], 9
	v_lshl_add_u64 v[4:5], s[78:79], 0, v[4:5]
	v_ashrrev_i32_e32 v7, 31, v6
	s_or_b32 s16, s16, s14
	v_lshl_add_u64 v[4:5], v[4:5], 0, s[38:39]
	v_lshlrev_b64 v[8:9], 1, v[6:7]
	s_add_u32 s0, s16, 0x10000
	v_ashrrev_i32_e32 v186, 3, v3
	v_lshlrev_b32_e32 v7, 3, v3
	v_lshl_add_u64 v[4:5], v[4:5], 0, v[8:9]
	s_addc_u32 s1, s17, 0
	v_and_b32_e32 v188, 56, v7
	v_ashrrev_i32_e32 v187, 31, v186
	global_load_dwordx4 v[114:117], v[4:5], off
	global_load_dwordx4 v[118:121], v[4:5], off offset:32
	global_load_dwordx4 v[122:125], v[4:5], off offset:64
	global_load_dwordx4 v[130:133], v[4:5], off offset:96
	v_or_b32_e32 v4, s0, v188
	v_mov_b32_e32 v5, s1
	v_lshlrev_b64 v[10:11], 9, v[186:187]
	v_lshl_add_u64 v[10:11], v[4:5], 0, v[10:11]
	v_lshlrev_b64 v[10:11], 1, v[10:11]
	v_add_u32_e32 v190, 8, v186
	v_lshl_add_u64 v[12:13], s[76:77], 0, v[10:11]
	v_lshl_add_u64 v[10:11], s[80:81], 0, v[10:11]
	v_ashrrev_i32_e32 v191, 31, v190
	global_load_dwordx4 v[126:129], v[12:13], off
	global_load_dwordx4 v[134:137], v[10:11], off
	v_lshlrev_b64 v[10:11], 9, v[190:191]
	v_lshl_add_u64 v[10:11], v[4:5], 0, v[10:11]
	v_lshlrev_b64 v[10:11], 1, v[10:11]
	v_add_u32_e32 v192, 16, v186
	v_lshl_add_u64 v[12:13], s[76:77], 0, v[10:11]
	v_lshl_add_u64 v[10:11], s[80:81], 0, v[10:11]
	v_ashrrev_i32_e32 v193, 31, v192
	global_load_dwordx4 v[138:141], v[12:13], off
	global_load_dwordx4 v[142:145], v[10:11], off
	v_lshlrev_b64 v[10:11], 9, v[192:193]
	v_lshl_add_u64 v[10:11], v[4:5], 0, v[10:11]
	v_lshlrev_b64 v[10:11], 1, v[10:11]
	v_add_u32_e32 v194, 24, v186
	v_lshl_add_u64 v[12:13], s[76:77], 0, v[10:11]
	v_lshl_add_u64 v[10:11], s[80:81], 0, v[10:11]
	v_ashrrev_i32_e32 v195, 31, v194
	global_load_dwordx4 v[146:149], v[12:13], off
	global_load_dwordx4 v[150:153], v[10:11], off
	v_lshlrev_b64 v[10:11], 9, v[194:195]
	v_lshl_add_u64 v[4:5], v[4:5], 0, v[10:11]
	v_lshlrev_b64 v[4:5], 1, v[4:5]
	v_lshl_add_u64 v[10:11], s[76:77], 0, v[4:5]
	v_lshl_add_u64 v[4:5], s[80:81], 0, v[4:5]
	global_load_dwordx4 v[154:157], v[10:11], off
	global_load_dwordx4 v[158:161], v[4:5], off
	v_cvt_f32_ubyte0_e32 v4, s3
	v_exp_f32_e64 v4, -v4
	v_xor_b32_e32 v5, v186, v3
	v_lshlrev_b32_e32 v5, 4, v5
	s_add_u32 s0, s78, s38
	v_mul_f32_e32 v229, 0x3fb8aa3b, v4
	v_lshlrev_b32_e32 v4, 7, v186
	v_and_or_b32 v4, v5, s50, v4
	v_lshlrev_b32_e32 v5, 2, v14
	v_lshrrev_b32_e32 v13, 2, v3
	s_addc_u32 s1, s79, 0
	v_and_or_b32 v13, v13, 3, v5
	v_lshl_add_u64 v[196:197], s[0:1], 0, v[8:9]
	v_bitop3_b32 v9, v14, v3, 7 bitop3:0x78
	v_add_u32_e32 v10, 2, v14
	v_add_u32_e32 v11, 4, v14
	v_add_u32_e32 v12, 6, v14
	v_lshlrev_b32_e32 v14, 7, v13
	v_and_b32_e32 v7, 8, v7
	v_add3_u32 v7, s73, v14, v7
	v_lshrrev_b32_e32 v14, 3, v3
	v_sub_u32_e32 v230, v5, v228
	v_and_b32_e32 v14, 2, v14
	v_bfe_u32 v15, v3, 1, 1
	v_cvt_f32_i32_e32 v231, v230
; #define LAS __attribute__((address_space(3)))
; DI s16x4 vtr(LAS const unsigned char* p) { return __builtin_bit_cast(s16x4, __builtin_amdgcn_ds_read_tr16_b64_v4i16((LAS v4i16_t*)p)); }
; #define MFMA32(a, b, c) __builtin_amdgcn_mfma_f32_32x32x16_bf16((a), (b), (c), 0, 0, 0)
; template <bool MASKED>
; DI void attn_tile_sw(int MODE, LAS const unsigned char* kst, LAS const unsigned char* vst, const bf16x8 (&qf)[4], float bstep, float ca, int lane, f32x16& o0, f32x16& o1, float& m, float& l) {
;     ...
;     f32x16 s; { const float sb = bstep * (float)(4 * hh - qq);
; #pragma unroll
;         for (int i = 0; i < 16; ++i) s[i] = bstep * (float)((i & 3) + 8 * (i >> 2)) + sb; }
;     {   bf16x8 kf[4];
; #pragma unroll
;         for (int st = 0; st < 4; ++st) kf[st] = *(LAS const bf16x8*)(kst + qq * 128 + (((2 * st + hh) ^ (qq & 7)) << 4));
; #pragma unroll
;         for (int st = 0; st < 4; ++st) s = MFMA32(kf[st], qf[st], s); }
;     const int q4 = (lane & 15) >> 2, p = lane & 3, blk = (lane >> 4) & 1, x = 4 * hh + q4;
;     LAS const unsigned char* vb = vst + x * 128 + 8 * (p & 1);
;     const int ch0 = ((2 * blk + (p >> 1)) ^ x) << 4, ch1 = ((4 + 2 * blk + (p >> 1)) ^ x) << 4;
;     const s16x4 va0 = vtr(vb + ch0), va1 = vtr(vb + 8 * 128 + ch0), vb0 = vtr(vb + ch1), vb1 = vtr(vb + 8 * 128 + ch1);
;     const s16x4 vc0 = vtr(vb + 16 * 128 + ch0), vc1 = vtr(vb + 24 * 128 + ch0), vd0 = vtr(vb + 16 * 128 + ch1), vd1 = vtr(vb + 24 * 128 + ch1);
;     if (MASKED) { const int dq = (MODE == 1) ? (qq - 4 * hh) : (4 * hh - qq);
; #pragma unroll
;         for (int r = 0; r < 16; ++r) { const int kq = (r & 3) + 8 * (r >> 2); s[r] = (((MODE == 1) ? kq : -kq) < dq) ? NEG : s[r]; } }
	v_or_b32_e32 v16, v14, v15
	v_bitop3_b32 v10, v10, v3, 7 bitop3:0x78
	v_bitop3_b32 v11, v11, v3, 7 bitop3:0x78
	v_bitop3_b32 v12, v12, v3, 7 bitop3:0x78
	v_bitop3_b32 v14, v14, v13, v15 bitop3:0x36
	v_bitop3_b32 v13, v16, v13, 4 bitop3:0x36
	v_lshl_add_u32 v8, v228, 7, s73
	v_lshlrev_b32_e32 v9, 4, v9
	v_lshlrev_b32_e32 v10, 4, v10
	v_lshlrev_b32_e32 v11, 4, v11
	v_lshlrev_b32_e32 v12, 4, v12
	v_lshlrev_b32_e32 v14, 4, v14
	v_lshlrev_b32_e32 v13, 4, v13
	s_mov_b32 s15, s39
	s_mov_b32 s44, 0
	v_mov_b32_e32 v189, v2
	v_sub_u32_e32 v232, v228, v5
	v_add_u32_e32 v233, 0, v6
	v_cmp_gt_u32_e64 s[6:7], 32, v3
	s_mov_b64 s[18:19], 0x200
	v_add_u32_e32 v234, s73, v4
	v_add_u32_e32 v235, v8, v9
	v_add_u32_e32 v236, v8, v10
	v_add_u32_e32 v237, v8, v11
	v_add_u32_e32 v238, v8, v12
	v_add_u32_e32 v239, v7, v14
	v_add_u32_e32 v240, v7, v13
	v_mov_b32_e32 v199, v229
	v_mov_b32_e32 v18, v231
	v_add_f32_e32 v19, 1.0, v231
	v_add_f32_e32 v20, 2.0, v231
	v_add_f32_e32 v21, 0x40400000, v231
	v_add_f32_e32 v22, 0x41000000, v231
	v_add_f32_e32 v23, 0x41100000, v231
	v_add_f32_e32 v24, 0x41200000, v231
	v_add_f32_e32 v25, 0x41300000, v231
	v_add_f32_e32 v26, 0x41800000, v231
	v_add_f32_e32 v27, 0x41880000, v231
	v_add_f32_e32 v28, 0x41900000, v231
	v_add_f32_e32 v29, 0x41980000, v231
	v_add_f32_e32 v30, 0x41c00000, v231
	v_add_f32_e32 v31, 0x41c80000, v231
	v_add_f32_e32 v32, 0x41d00000, v231
	v_add_f32_e32 v33, 0x41d80000, v231
	v_cmp_le_i32_e32 vcc, 0, v232
	v_cmp_ge_i32_e64 s[26:27], 0, v232
	v_cmp_le_i32_e64 s[2:3], 1, v232
	v_cndmask_b32_e32 v34, v226, v18, vcc
	v_cmp_ge_i32_e32 vcc, 1, v232
	v_cndmask_b32_e64 v50, v226, v18, s[26:27]
	v_cmp_le_i32_e64 s[26:27], 2, v232
	v_cndmask_b32_e64 v35, v226, v19, s[2:3]
	v_cmp_ge_i32_e64 s[2:3], 2, v232
	v_cndmask_b32_e32 v51, v226, v19, vcc
	v_cmp_le_i32_e32 vcc, 3, v232
	v_cndmask_b32_e64 v36, v226, v20, s[26:27]
	v_cmp_ge_i32_e64 s[26:27], 3, v232
	v_cndmask_b32_e64 v52, v226, v20, s[2:3]
	v_cmp_le_i32_e64 s[2:3], 8, v232
	v_cndmask_b32_e32 v37, v226, v21, vcc
	v_cmp_ge_i32_e32 vcc, 8, v232
	v_cndmask_b32_e64 v53, v226, v21, s[26:27]
	v_cmp_le_i32_e64 s[26:27], 9, v232
	v_cndmask_b32_e64 v38, v226, v22, s[2:3]
	v_cmp_ge_i32_e64 s[2:3], 9, v232
	v_cndmask_b32_e32 v54, v226, v22, vcc
	v_cmp_le_i32_e32 vcc, 10, v232
	v_cndmask_b32_e64 v39, v226, v23, s[26:27]
	v_cmp_ge_i32_e64 s[26:27], 10, v232
	v_cndmask_b32_e64 v55, v226, v23, s[2:3]
	v_cmp_le_i32_e64 s[2:3], 11, v232
	v_cndmask_b32_e32 v40, v226, v24, vcc
	v_cmp_ge_i32_e32 vcc, 11, v232
	v_cndmask_b32_e64 v56, v226, v24, s[26:27]
	v_cmp_le_i32_e64 s[26:27], 16, v232
	v_cndmask_b32_e64 v41, v226, v25, s[2:3]
	v_cmp_ge_i32_e64 s[2:3], 16, v232
	v_cndmask_b32_e32 v57, v226, v25, vcc
	v_cmp_le_i32_e32 vcc, 17, v232
	v_cndmask_b32_e64 v42, v226, v26, s[26:27]
	v_cmp_ge_i32_e64 s[26:27], 17, v232
	v_cndmask_b32_e64 v58, v226, v26, s[2:3]
	v_cmp_le_i32_e64 s[2:3], 18, v232
	v_cndmask_b32_e32 v43, v226, v27, vcc
	v_cmp_ge_i32_e32 vcc, 18, v232
	v_cndmask_b32_e64 v59, v226, v27, s[26:27]
	v_cmp_le_i32_e64 s[26:27], 19, v232
	v_cndmask_b32_e64 v44, v226, v28, s[2:3]
	v_cmp_ge_i32_e64 s[2:3], 19, v232
	v_cndmask_b32_e32 v60, v226, v28, vcc
	v_cmp_le_i32_e32 vcc, 24, v232
	v_cndmask_b32_e64 v45, v226, v29, s[26:27]
	v_cmp_ge_i32_e64 s[26:27], 24, v232
	v_cndmask_b32_e64 v61, v226, v29, s[2:3]
	v_cmp_le_i32_e64 s[2:3], 25, v232
	v_cndmask_b32_e32 v46, v226, v30, vcc
	v_cmp_ge_i32_e32 vcc, 25, v232
	v_cndmask_b32_e64 v62, v226, v30, s[26:27]
	v_cmp_le_i32_e64 s[26:27], 26, v232
	v_cndmask_b32_e64 v47, v226, v31, s[2:3]
	v_cmp_ge_i32_e64 s[2:3], 26, v232
	v_cndmask_b32_e32 v63, v226, v31, vcc
	v_cmp_le_i32_e32 vcc, 27, v232
	v_cndmask_b32_e64 v48, v226, v32, s[26:27]
	v_cmp_ge_i32_e64 s[26:27], 27, v232
	v_cndmask_b32_e64 v64, v226, v32, s[2:3]
	v_cndmask_b32_e32 v49, v226, v33, vcc
	v_cndmask_b32_e64 v65, v226, v33, s[26:27]
	s_branch .LBB0_755

; DI void unit_dilated2(int u, const bf16* __restrict__ Q, const bf16* __restrict__ K, const bf16* __restrict__ V, const bf16* __restrict__ G, bf16* __restrict__ MIX, LAS unsigned char* lds, int tid, int lane, int wave) {
;     ...
;     for (int seq = 0; seq < 6; ++seq) {
;         const DilWT nw = dil_wt(seq < 5 ? seq + 1 : 5, wave, b, h, T0, qq, slope2);
;         bf16x8 qn[4];
; #pragma unroll
;         for (int st = 0; st < 4; ++st) qn[st] = *(const bf16x8*)(Q + nw.qrow * 512 + h * 64 + 16 * st + 8 * hh);
;         f32x16 o0, o1;
; #pragma unroll
;         for (int i = 0; i < 16; ++i) { o0[i] = 0.f; o1[i] = 0.f; }
;         float m = NEG, l = 0.f;
; #pragma unroll 1
;         for (int a = 4; a >= cw.a0; --a) {
;             dil_store(kst, vst, kr, vr, lane);
;             if (a > cw.a0) dil_load(kr, vr, K, V, cw.rb0 + (long)(32 * (a - 1)) * cw.gstride, cw.gstride, lane);
;             else if (seq < 5) dil_load(kr, vr, K, V, nw.rb0 + (long)(32 * 4) * nw.gstride, nw.gstride, lane);
;             const float ca = -cw.bstep * (float)(128 - 32 * a);
.LBB0_755:
	s_mov_b32 s35, s44
	s_add_i32 s44, s44, 1
	s_cmp_lg_u32 s35, 5
	s_cselect_b64 s[22:23], -1, 0
	s_and_b64 s[0:1], s[22:23], exec
	s_cselect_b32 s0, s44, 5
	s_lshl_b32 s1, s0, 3
	s_and_b32 s1, s1, 8
	s_and_b32 s0, s0, 14
	s_add_i32 s1, s1, s33
	s_sub_i32 s8, 4, s0
	s_mov_b64 s[2:3], s[16:17]
	s_lshr_b32 s16, s1, s8
	s_lshr_b32 s8, 16, s0
	s_add_i32 s8, s8, -1
	s_and_b32 s1, s1, s8
	s_lshl_b32 s9, s1, 5
	v_or_b32_e32 v3, s9, v228
	v_lshlrev_b32_e32 v3, s0, v3
	v_mov_b32_e32 v241, v184
	v_add_u32_e32 v184, s16, v3
	v_ashrrev_i32_e32 v185, 31, v184
	v_lshl_add_u64 v[4:5], s[10:11], 0, v[184:185]
	v_lshlrev_b64 v[4:5], 10, v[4:5]
	s_waitcnt vmcnt(0)
	v_mov_b64_e32 v[164:165], v[132:133]
	v_mov_b64_e32 v[168:169], v[124:125]
	v_mov_b64_e32 v[172:173], v[120:121]
	v_mov_b64_e32 v[176:177], v[116:117]
	v_lshl_add_u64 v[4:5], v[196:197], 0, v[4:5]
	v_mov_b64_e32 v[162:163], v[130:131]
	v_mov_b64_e32 v[166:167], v[122:123]
	v_mov_b64_e32 v[170:171], v[118:119]
	v_mov_b64_e32 v[174:175], v[114:115]
	global_load_dwordx4 v[114:117], v[4:5], off
	global_load_dwordx4 v[118:121], v[4:5], off offset:32
	global_load_dwordx4 v[122:125], v[4:5], off offset:64
	global_load_dwordx4 v[130:133], v[4:5], off offset:96
	s_lshr_b32 s8, s34, s0
	s_add_i32 s1, s9, s8
	s_add_i32 s8, s1, 0xffffff80
	s_ashr_i32 s9, s8, 31
	s_lshl_b32 s38, 0x200, s0
	s_lshl_b64 s[8:9], s[8:9], s0
	s_add_u32 s16, s12, s16
	s_addc_u32 s17, s13, 0
	s_add_u32 s8, s16, s8
	s_addc_u32 s9, s17, s9
	s_lshl_b64 s[8:9], s[8:9], 9
	s_or_b64 s[16:17], s[8:9], s[14:15]
	s_mov_b64 s[20:21], s[18:19]
	s_mov_b64 s[18:19], s[38:39]
	v_mov_b32_e32 v5, s17
	v_or_b32_e32 v4, s16, v188
	s_lshl_b32 s38, s38, 7
	s_add_i32 s8, s0, 9
	v_lshl_add_u64 v[4:5], v[4:5], 0, s[38:39]
	v_lshlrev_b64 v[6:7], s8, v[186:187]
	v_lshl_add_u64 v[6:7], v[4:5], 0, v[6:7]
	v_lshlrev_b64 v[6:7], 1, v[6:7]
	v_lshl_add_u64 v[200:201], s[76:77], 0, v[6:7]
	v_lshl_add_u64 v[202:203], s[80:81], 0, v[6:7]
	v_lshlrev_b64 v[6:7], s8, v[190:191]
	v_lshl_add_u64 v[6:7], v[4:5], 0, v[6:7]
	v_lshlrev_b64 v[6:7], 1, v[6:7]
	v_lshl_add_u64 v[204:205], s[76:77], 0, v[6:7]
	v_lshl_add_u64 v[206:207], s[80:81], 0, v[6:7]
	v_lshlrev_b64 v[6:7], s8, v[192:193]
	v_lshl_add_u64 v[6:7], v[4:5], 0, v[6:7]
	v_lshlrev_b64 v[6:7], 1, v[6:7]
	v_lshl_add_u64 v[208:209], s[76:77], 0, v[6:7]
	v_lshl_add_u64 v[210:211], s[80:81], 0, v[6:7]
	v_lshlrev_b64 v[6:7], s8, v[194:195]
	v_lshl_add_u64 v[4:5], v[4:5], 0, v[6:7]
	v_lshlrev_b64 v[4:5], 1, v[4:5]
	v_lshl_add_u64 v[212:213], s[76:77], 0, v[4:5]
	v_lshl_add_u64 v[214:215], s[80:81], 0, v[4:5]
	v_mul_lo_u32 v216, s20, v186
	s_mul_i32 s8, s20, 0x60
	s_add_u32 s8, s2, s8
	s_addc_u32 s9, s3, 0
	s_lshl_b64 s[8:9], s[8:9], 1
	s_add_u32 s8, s8, s76
	s_addc_u32 s9, s9, s77
	s_sub_u32 s3, s80, s76
	s_lshl_b32 s2, s20, 4
	v_add_lshl_u32 v216, v216, v188, 1
	v_add_u32_e32 v217, s2, v216
	v_add_u32_e32 v218, s2, v217
	v_add_u32_e32 v219, s2, v218
	v_add_u32_e32 v220, s3, v216
	v_add_u32_e32 v221, s3, v217
	v_add_u32_e32 v222, s3, v218
	v_add_u32_e32 v223, s3, v219
	v_mul_f32_e32 v4, v199, v231
	v_mul_f32_e32 v198, 0, v199
	v_mov_b32_e32 v6, v199
	v_mov_b32_e32 v16, v2
	v_mov_b32_e32 v17, v2
	v_pk_add_f32 v[18:19], v[198:199], v[4:5] op_sel_hi:[1,0]
	v_pk_fma_f32 v[20:21], v[6:7], s[96:97], v[4:5] op_sel_hi:[0,1,0]
	v_pk_fma_f32 v[22:23], v[6:7], s[74:75], v[4:5] op_sel_hi:[0,1,0]
	v_pk_fma_f32 v[24:25], v[6:7], s[82:83], v[4:5] op_sel_hi:[0,1,0]
	v_pk_fma_f32 v[26:27], v[6:7], s[86:87], v[4:5] op_sel_hi:[0,1,0]
	v_pk_fma_f32 v[28:29], v[6:7], s[90:91], v[4:5] op_sel_hi:[0,1,0]
	v_pk_fma_f32 v[30:31], v[6:7], s[68:69], v[4:5] op_sel_hi:[0,1,0]
	v_pk_fma_f32 v[32:33], v[6:7], s[70:71], v[4:5] op_sel_hi:[0,1,0]
	s_lshl_b32 s2, s20, 6
	s_mov_b32 s31, 4
	s_mov_b32 s51, 0
	v_mov_b32_e32 v198, 0xf149f2ca
	v_mov_b32_e32 v185, 0

; #define LAS __attribute__((address_space(3)))
; DI s16x4 vtr(LAS const unsigned char* p) { return __builtin_bit_cast(s16x4, __builtin_amdgcn_ds_read_tr16_b64_v4i16((LAS v4i16_t*)p)); }
; #define MFMA32(a, b, c) __builtin_amdgcn_mfma_f32_32x32x16_bf16((a), (b), (c), 0, 0, 0)
; template <bool MASKED>
; DI void attn_tile_sw(int MODE, LAS const unsigned char* kst, LAS const unsigned char* vst, const bf16x8 (&qf)[4], float bstep, float ca, int lane, f32x16& o0, f32x16& o1, float& m, float& l) {
;     ...
;     f32x16 s; { const float sb = bstep * (float)(4 * hh - qq);
; #pragma unroll
;         for (int i = 0; i < 16; ++i) s[i] = bstep * (float)((i & 3) + 8 * (i >> 2)) + sb; }
;     {   bf16x8 kf[4];
; #pragma unroll
;         for (int st = 0; st < 4; ++st) kf[st] = *(LAS const bf16x8*)(kst + qq * 128 + (((2 * st + hh) ^ (qq & 7)) << 4));
; #pragma unroll
;         for (int st = 0; st < 4; ++st) s = MFMA32(kf[st], qf[st], s); }
;     const int q4 = (lane & 15) >> 2, p = lane & 3, blk = (lane >> 4) & 1, x = 4 * hh + q4;
;     LAS const unsigned char* vb = vst + x * 128 + 8 * (p & 1);
;     const int ch0 = ((2 * blk + (p >> 1)) ^ x) << 4, ch1 = ((4 + 2 * blk + (p >> 1)) ^ x) << 4;
;     const s16x4 va0 = vtr(vb + ch0), va1 = vtr(vb + 8 * 128 + ch0), vb0 = vtr(vb + ch1), vb1 = vtr(vb + 8 * 128 + ch1);
;     const s16x4 vc0 = vtr(vb + 16 * 128 + ch0), vc1 = vtr(vb + 24 * 128 + ch0), vd0 = vtr(vb + 16 * 128 + ch1), vd1 = vtr(vb + 24 * 128 + ch1);
;     if (MASKED) { const int dq = (MODE == 1) ? (qq - 4 * hh) : (4 * hh - qq);
; #pragma unroll
;         for (int r = 0; r < 16; ++r) { const int kq = (r & 3) + 8 * (r >> 2); s[r] = (((MODE == 1) ? kq : -kq) < dq) ? NEG : s[r]; } }
.Ldil_qk_m2:
	v_pk_mul_f32 v[98:99], v[34:35], v[198:199] op_sel:[0,1] op_sel_hi:[1,1]
	v_pk_mul_f32 v[100:101], v[36:37], v[198:199] op_sel:[0,1] op_sel_hi:[1,1]
	v_pk_mul_f32 v[102:103], v[38:39], v[198:199] op_sel:[0,1] op_sel_hi:[1,1]
	v_pk_mul_f32 v[104:105], v[40:41], v[198:199] op_sel:[0,1] op_sel_hi:[1,1]
	v_pk_mul_f32 v[106:107], v[42:43], v[198:199] op_sel:[0,1] op_sel_hi:[1,1]
	v_pk_mul_f32 v[108:109], v[44:45], v[198:199] op_sel:[0,1] op_sel_hi:[1,1]
	v_pk_mul_f32 v[110:111], v[46:47], v[198:199] op_sel:[0,1] op_sel_hi:[1,1]
	v_pk_mul_f32 v[112:113], v[48:49], v[198:199] op_sel:[0,1] op_sel_hi:[1,1]
	s_waitcnt lgkmcnt(1)
	s_nop 1
	v_mfma_f32_32x32x16_bf16 v[98:113], v[4:7], v[174:177], v[98:113]
	s_branch .Ldil_qk_join
.Ldil_qk_m1:
	v_pk_mul_f32 v[98:99], v[50:51], v[198:199] op_sel:[0,1] op_sel_hi:[1,1]
	v_pk_mul_f32 v[100:101], v[52:53], v[198:199] op_sel:[0,1] op_sel_hi:[1,1]
	v_pk_mul_f32 v[102:103], v[54:55], v[198:199] op_sel:[0,1] op_sel_hi:[1,1]
	v_pk_mul_f32 v[104:105], v[56:57], v[198:199] op_sel:[0,1] op_sel_hi:[1,1]
	v_pk_mul_f32 v[106:107], v[58:59], v[198:199] op_sel:[0,1] op_sel_hi:[1,1]
	v_pk_mul_f32 v[108:109], v[60:61], v[198:199] op_sel:[0,1] op_sel_hi:[1,1]
	v_pk_mul_f32 v[110:111], v[62:63], v[198:199] op_sel:[0,1] op_sel_hi:[1,1]
	v_pk_mul_f32 v[112:113], v[64:65], v[198:199] op_sel:[0,1] op_sel_hi:[1,1]
	s_waitcnt lgkmcnt(1)
	s_nop 1
	v_mfma_f32_32x32x16_bf16 v[98:113], v[4:7], v[174:177], v[98:113]
